# C-mixer (forgetting attention) loop unrolled 2x with ping-pong score registers: removes 8 v_mov_b64 + 32 v_cndmask copies and 8 redundant x0/x1 zeroing selects per tile
# speedup vs baseline: 1.0551x; 1.0132x over previous
; #define LAS __attribute__((address_space(3)))
; #define ATT_WAIT_BAR() asm volatile("s_waitcnt vmcnt(0) lgkmcnt(0)\n\ts_barrier" ::: "memory")
; template <int KIND> DI void attn_unit(const Params& P, int b, int h, int qb, char* shm, float lam, bool dry = false) {
;     ...
;     bf16x8 ones = (bf16x8){0, 0, 0, 0, 0, 0, 0, 0}; if (KIND == 2 && hi == 0) { ones[0] = 0x3F80; ones[1] = 0x3F80; ones[2] = 0x3F80; }
;     float mhat = 0.f, lsum = 0.f; f32x16 o[NDB]; f32x16 negm;
; #pragma unroll
;     for (int i = 0; i < NDB; ++i) o[i] = f32x16{};
; #pragma unroll
;     for (int r = 0; r < 16; ++r) negm[r] = cb;
;     const int vlane = ((lane >> 4) & 1) * 32 + (lane & 3) * 8 + (4 * hi + ((lane & 15) >> 2)) * 64;
;     LAS unsigned* vote = (LAS unsigned*)(shm3 + OFF_VOTE);
;     if (KIND == 2 && tid < 32) vote[tid] = 0u;
;     ATT_WAIT_BAR();
;     int sc = 0, sd = 3 * SLOT;
;     int nt_eff = NT;
.LBB0_340:
	s_lshl_b32 s4, s8, 2
	s_add_i32 s37, s4, 0
	v_lshlrev_b32_e32 v37, 1, v53
	s_add_i32 s36, s18, s33
	s_add_i32 s19, s33, 4
	s_add_i32 s37, s37, 0x23240
	s_sub_i32 s40, 3, s18
	v_and_b32_e32 v170, 32, v37
	v_lshlrev_b32_e32 v37, 3, v53
	s_cmp_lg_u32 0, -1
	v_and_b32_e32 v171, 24, v37
	v_lshrrev_b32_e32 v37, 2, v53
	s_cselect_b32 s4, 0, 0
	v_and_or_b32 v37, v37, 3, v56
	s_add_i32 s41, s41, s4
	s_mov_b32 s25, 24
	v_lshlrev_b32_e32 v172, 6, v37
	s_mov_b32 s35, 0
	s_add_i32 s23, s41, 0x4000
	v_add_f32_e32 v202, v54, v36
	v_cmp_eq_u32_e64 s[46:47], 0, v52
	v_cmp_gt_u32_e64 s[48:49], v56, v55
	v_cmp_gt_u32_e64 s[50:51], v58, v55
	v_cmp_lt_u32_e64 s[52:53], v56, v55
	v_cmp_gt_u32_e64 s[54:55], v57, v55
	v_cmp_gt_u32_e64 s[56:57], v59, v55
	v_cmp_gt_u32_e64 s[58:59], v60, v55
	v_cmp_gt_u32_e64 s[60:61], v61, v55
	v_cmp_gt_u32_e64 s[62:63], v62, v55
	v_cmp_gt_u32_e64 s[64:65], v63, v55
	v_cmp_gt_u32_e64 s[66:67], v64, v55
	v_cmp_gt_u32_e64 s[68:69], v65, v55
	v_cmp_gt_u32_e64 s[70:71], v66, v55
	v_cmp_gt_u32_e64 s[72:73], v67, v55
	v_cmp_gt_u32_e64 s[74:75], v84, v55
	v_cmp_gt_u32_e64 s[76:77], v85, v55
	v_cmp_gt_u32_e64 s[78:79], v86, v55
	v_cmp_gt_u32_e64 s[80:81], v87, v55
	v_cmp_gt_u32_e64 s[82:83], v88, v55
	v_cmp_gt_u32_e64 s[84:85], v90, v55
	v_cmp_gt_u32_e64 s[86:87], v91, v55
	v_cmp_gt_u32_e64 s[88:89], v92, v55
	v_cmp_gt_u32_e64 s[90:91], v93, v55
	v_cmp_gt_u32_e64 s[92:93], v94, v55
	v_cmp_gt_u32_e64 s[94:95], v95, v55
	v_cmp_gt_u32_e64 s[96:97], v102, v55
	v_cmp_gt_u32_e64 s[4:5], v89, v55
	v_cmp_gt_u32_e64 s[6:7], v96, v55
	v_cmp_gt_u32_e64 s[8:9], v97, v55
	v_cmp_gt_u32_e64 s[10:11], v98, v55
	v_cmp_gt_u32_e64 s[12:13], v99, v55
	v_cmp_gt_u32_e64 s[14:15], v100, v55
	v_cmp_gt_u32_e64 s[16:17], v101, v55
	s_sub_i32 s22, 2, s18
	s_mov_b32 s30, 0x18c00
	v_mov_b32_e32 v173, s19
	s_mov_b32 s20, s33
	s_mov_b32 s34, 0
	v_mov_b32_e32 v52, v169
	v_mov_b32_e32 v53, v169
	v_mov_b32_e32 v54, v169
	v_mov_b32_e32 v55, v169
	v_mov_b32_e32 v56, v169
	v_mov_b32_e32 v57, v169
	v_mov_b32_e32 v58, v169
	v_mov_b32_e32 v59, v169
	v_mov_b32_e32 v60, v169
	v_mov_b32_e32 v61, v169
	v_mov_b32_e32 v62, v169
	v_mov_b32_e32 v63, v169
	v_mov_b32_e32 v64, v169
	v_mov_b32_e32 v65, v169
	v_mov_b32_e32 v66, v169
	v_mov_b32_e32 v67, v169
	v_mov_b32_e32 v36, v169
	v_mov_b32_e32 v37, v169
	v_mov_b32_e32 v38, v169
	v_mov_b32_e32 v39, v169
	v_mov_b32_e32 v40, v169
	v_mov_b32_e32 v41, v169
	v_mov_b32_e32 v42, v169
	v_mov_b32_e32 v43, v169
	v_mov_b32_e32 v44, v169
	v_mov_b32_e32 v45, v169
	v_mov_b32_e32 v46, v169
	v_mov_b32_e32 v47, v169
	v_mov_b32_e32 v48, v169
	v_mov_b32_e32 v49, v169
	v_mov_b32_e32 v50, v169
	v_mov_b32_e32 v51, v169
	v_mov_b32_e32 v116, v68
	v_mov_b32_e32 v117, v69
	v_mov_b32_e32 v118, v70
	v_mov_b32_e32 v119, v71
	v_mov_b32_e32 v120, v72
	v_mov_b32_e32 v121, v73
	v_mov_b32_e32 v122, v74
	v_mov_b32_e32 v123, v75
	v_mov_b32_e32 v124, v76
	v_mov_b32_e32 v125, v77
	v_mov_b32_e32 v126, v78
	v_mov_b32_e32 v127, v79
	v_mov_b32_e32 v128, v80
	v_mov_b32_e32 v129, v81
	v_mov_b32_e32 v130, v82
	v_mov_b32_e32 v131, v83

; #define SBAR() __builtin_amdgcn_sched_barrier(0)
; #define PIN(x) asm volatile("" : "+v"(x))
; #define MF(a_, b_, c_) __builtin_amdgcn_mfma_f32_32x32x16_bf16(a_, b_, c_, 0, 0, 0)
; #define PVM(j_) o[(j_) % NDB] = MF(vq[(j_) & 3], pw[(j_) / NDB], o[(j_) % NDB])
; template <int KIND> DI void attn_unit(const Params& P, int b, int h, int qb, char* shm, float lam, bool dry = false) {
;     ...
;         ATT_KLD(sn, 0); ATT_XLD(sn);
;         SBAR();
;     ...
;         G1(pb0 = MF(kf[0], qr[0], negm), 0, w0, 0);  G1(pb1 = MF(kf[1], qr[0], negm), 2, w0, 1);
;         G1(pb0 = MF(kf[2], qr[1], pb0), 4, w0, 2);   G1(pb1 = MF(kf[3], qr[1], pb1), 6, w0, 3);
;         ATT_KLD(sn, 1);
;         SBAR();
;         G1(pb0 = MF(kf[0], qr[2], pb0), 8, w1, 0);   G1(pb1 = MF(kf[1], qr[2], pb1), 10, w1, 1);
;         LDV(0); SBAR();
;         G1(pb0 = MF(kf[2], qr[3], pb0), 12, w1, 2);
;         LDV(1); SBAR();
;         G1(pb1 = MF(kf[3], qr[3], pb1), 14, w1, 3);
;         LDV(2); SBAR();
;     ...
;         if (KIND == 2) { pb0 = MF(x0, ones, pb0); pb1 = MF(x1, ones, pb1); }
;         pw[0] = __builtin_bit_cast(bf16x8, w0); pw[1] = __builtin_bit_cast(bf16x8, w1);
;     ...
;         if (NDB == 4) {
;             LDV(3); PVM(0); E4(0, w0, 0); PIN(pa1); PIN(sacc); PIN(w0); SBAR();
;             LDV(4); PVM(1); E4(2, w0, 1); PIN(pa1); PIN(sacc); PIN(w0); SBAR();
;             LDV(5); PVM(2); E4(4, w0, 2); PIN(pa1); PIN(sacc); PIN(w0); SBAR();
;             LDV(6); PVM(3); E4(6, w0, 3); PIN(pa1); PIN(sacc); PIN(w0); SBAR();
;             LDV(7); PVM(4); E4(8, w1, 0); PIN(pa1); PIN(sacc); PIN(w1); SBAR();
;             LDV(8); PVM(5); E4(10, w1, 1); PIN(pa1); PIN(sacc); PIN(w1); SBAR();
;             LDV(9); PVM(6); E4(12, w1, 2); PIN(pa1); PIN(sacc); PIN(w1); SBAR();
;             LDV(10); PVM(7); E4(14, w1, 3); PIN(pa1); PIN(sacc); PIN(w1); SBAR();
;         } else {
;             LDV(3); PVM(0); E4(0, w0, 0); E4(2, w0, 1); PIN(pa1); PIN(sacc); PIN(w0); SBAR();
;             LDV(4); PVM(1); E4(4, w0, 2); E4(6, w0, 3); PIN(pa1); PIN(sacc); PIN(w0); SBAR();
;             LDV(5); PVM(2); E4(8, w1, 0); E4(10, w1, 1); PIN(pa1); PIN(sacc); PIN(w1); SBAR();
;             LDV(6); PVM(3); E4(12, w1, 2); E4(14, w1, 3); PIN(pa1); PIN(sacc); PIN(w1); SBAR();
;         }
;     ...
;         pw[2] = __builtin_bit_cast(bf16x8, w0); pw[3] = __builtin_bit_cast(bf16x8, w1);
;         lsum += sacc;
;         ATT_FIX(pb0, pb1, ATT_TILE(i + 1));
.LBB0_355:
	s_add_i32 s18, s34, 0x8400
	s_cmp_lg_u32 s34, 0x18c00
	s_cselect_b32 s29, s18, 0
	s_add_i32 s18, s29, 0
	v_add_u32_e32 v84, s18, v168
	v_add_u32_e32 v186, v84, v167
	ds_read_b128 v[100:103], v186
	ds_read_b128 v[174:177], v186 offset:512
	ds_read_b128 v[178:181], v186 offset:2048
	ds_read_b128 v[182:185], v186 offset:2560
	ds_read_b128 v[190:193], v84 offset:32768
	ds_read_b128 v[196:199], v84 offset:33280
	v_exp_f32_e32 v116, v116
	v_exp_f32_e32 v117, v117
	s_nop 0
	v_cvt_pk_bf16_f32 v152, v116, v117
	v_add_f32_e32 v84, 0, v116
	v_add_f32_e32 v84, v117, v84
	s_nop 0
	v_exp_f32_e32 v118, v118
	v_exp_f32_e32 v119, v119
	v_add_f32_e32 v84, v84, v118
	v_add_f32_e32 v84, v119, v84
	v_cvt_pk_bf16_f32 v153, v118, v119
	s_nop 0
	v_exp_f32_e32 v120, v120
	v_exp_f32_e32 v121, v121
	v_add_f32_e32 v84, v84, v120
	v_add_f32_e32 v187, v121, v84
	v_cvt_pk_bf16_f32 v154, v120, v121
	s_waitcnt lgkmcnt(5)
	v_mfma_f32_32x32x16_bf16 v[84:99], v[100:103], v[144:147], v[20:35]
	v_exp_f32_e32 v122, v122
	v_exp_f32_e32 v123, v123
	s_waitcnt lgkmcnt(4)
	v_mfma_f32_32x32x16_bf16 v[100:115], v[174:177], v[144:147], v[20:35]
	s_add_i32 s18, s34, 0
	v_exp_f32_e32 v124, v124
	v_exp_f32_e32 v125, v125
	s_waitcnt lgkmcnt(3)
	v_mfma_f32_32x32x16_bf16 v[84:99], v[178:181], v[140:143], v[84:99]
	v_add3_u32 v68, s18, v170, v171
	v_add_f32_e32 v72, v187, v122
	v_cvt_pk_bf16_f32 v148, v124, v125
	v_add_u32_e32 v164, v68, v172
	s_waitcnt lgkmcnt(0)
	v_add_f32_e32 v187, v123, v72
	v_cvt_pk_bf16_f32 v155, v122, v123
	v_mfma_f32_32x32x16_bf16 v[100:115], v[182:185], v[140:143], v[100:115]
	ds_read_b128 v[72:75], v186 offset:4096
	ds_read_b128 v[80:83], v186 offset:4608
	ds_read_b128 v[174:177], v186 offset:6144
	ds_read_b128 v[178:181], v186 offset:6656
	s_waitcnt lgkmcnt(3)
	v_mfma_f32_32x32x16_bf16 v[84:99], v[72:75], v[136:139], v[84:99]
	v_add_f32_e32 v72, v187, v124
	v_add_f32_e32 v72, v125, v72
	s_waitcnt lgkmcnt(2)
	v_mfma_f32_32x32x16_bf16 v[100:115], v[80:83], v[136:139], v[100:115]
	v_exp_f32_e32 v126, v126
	v_exp_f32_e32 v127, v127
	v_add_f32_e32 v72, v72, v126
	v_add_f32_e32 v80, v127, v72
	v_cvt_pk_bf16_f32 v149, v126, v127
	ds_read_b64_tr_b16 v[72:73], v164 offset:16384
	ds_read_b64_tr_b16 v[74:75], v164 offset:16896
	s_waitcnt lgkmcnt(3)
	v_mfma_f32_32x32x16_bf16 v[84:99], v[174:177], v[132:135], v[84:99]
	v_exp_f32_e32 v128, v128
	v_exp_f32_e32 v129, v129
	v_add_f32_e32 v80, v80, v128
	v_add_f32_e32 v174, v129, v80
	v_cvt_pk_bf16_f32 v150, v128, v129
	ds_read_b64_tr_b16 v[80:81], v164 offset:20480
	ds_read_b64_tr_b16 v[82:83], v164 offset:20992
	s_waitcnt lgkmcnt(4)
	v_mfma_f32_32x32x16_bf16 v[100:115], v[178:181], v[132:135], v[100:115]
	v_exp_f32_e32 v130, v130
	v_exp_f32_e32 v131, v131
	v_add_f32_e32 v151, v174, v130
	v_add_f32_e32 v174, v131, v151
	v_cvt_pk_bf16_f32 v151, v130, v131
	ds_read_b64_tr_b16 v[124:125], v164 offset:17408
	ds_read_b64_tr_b16 v[126:127], v164 offset:17920
	v_mfma_f32_32x32x16_bf16 v[84:99], v[190:193], v[0:3], v[84:99]
	v_exp_f32_e32 v4, v4
	v_exp_f32_e32 v5, v5
	v_exp_f32_e32 v6, v6
	v_exp_f32_e32 v7, v7
	v_cvt_pk_bf16_f32 v77, v4, v5
	v_mfma_f32_32x32x16_bf16 v[100:115], v[196:199], v[0:3], v[100:115]
	ds_read_b64_tr_b16 v[68:69], v164 offset:21504
	ds_read_b64_tr_b16 v[70:71], v164 offset:22016
	s_waitcnt lgkmcnt(6)
	v_mfma_f32_32x32x16_bf16 v[52:67], v[72:75], v[152:155], v[52:67]
	v_add_f32_e32 v72, v4, v174
	v_add_f32_e32 v76, v5, v72
	v_mov_b64_e32 v[72:73], v[152:153]
	v_add_f32_e32 v73, v6, v76
	v_mov_b64_e32 v[74:75], v[154:155]
	v_mov_b32_e32 v72, v77
	v_add_f32_e32 v76, v7, v73
	v_cvt_pk_bf16_f32 v73, v6, v7
	s_nop 0
	v_exp_f32_e32 v8, v8
	v_exp_f32_e32 v9, v9
	s_waitcnt lgkmcnt(4)
	v_mfma_f32_32x32x16_bf16 v[36:51], v[80:83], v[152:155], v[36:51]
	v_exp_f32_e32 v10, v10
	v_exp_f32_e32 v11, v11
	v_add_f32_e32 v74, v76, v8
	ds_read_b64_tr_b16 v[116:117], v164 offset:18432
	ds_read_b64_tr_b16 v[118:119], v164 offset:18944
	v_add_f32_e32 v75, v9, v74
	v_add_f32_e32 v75, v10, v75
	v_cvt_pk_bf16_f32 v74, v8, v9
	v_add_f32_e32 v76, v11, v75
	v_cvt_pk_bf16_f32 v75, v10, v11
	v_mov_b64_e32 v[154:155], v[74:75]
	v_mov_b64_e32 v[152:153], v[72:73]
	s_nop 0
	v_exp_f32_e32 v12, v12
	s_waitcnt lgkmcnt(4)
	v_mfma_f32_32x32x16_bf16 v[52:67], v[124:127], v[148:151], v[52:67]
	v_exp_f32_e32 v13, v13
	v_exp_f32_e32 v14, v14
	ds_read_b64_tr_b16 v[120:121], v164 offset:22528
	ds_read_b64_tr_b16 v[122:123], v164 offset:23040
	v_exp_f32_e32 v15, v15
	v_add_f32_e32 v72, v76, v12
	v_add_f32_e32 v76, v13, v72
	v_mov_b64_e32 v[72:73], v[148:149]
	v_cvt_pk_bf16_f32 v77, v12, v13
	v_add_f32_e32 v73, v14, v76
	v_mov_b64_e32 v[74:75], v[150:151]
	v_mov_b32_e32 v72, v77
	v_add_f32_e32 v76, v15, v73
	v_cvt_pk_bf16_f32 v73, v14, v15
	s_waitcnt lgkmcnt(4)
	v_mfma_f32_32x32x16_bf16 v[36:51], v[68:71], v[148:151], v[36:51]
	v_exp_f32_e32 v16, v16
	v_exp_f32_e32 v17, v17
	v_exp_f32_e32 v18, v18
	v_exp_f32_e32 v19, v19
	ds_read_b64_tr_b16 v[124:125], v164 offset:19456
	ds_read_b64_tr_b16 v[126:127], v164 offset:19968
	v_add_f32_e32 v68, v76, v16
	v_add_f32_e32 v68, v17, v68
	v_cvt_pk_bf16_f32 v74, v16, v17
	v_cvt_pk_bf16_f32 v75, v18, v19
	v_add_f32_e32 v68, v18, v68
	v_mov_b64_e32 v[150:151], v[74:75]
	v_add_f32_e32 v68, v19, v68
	v_mov_b64_e32 v[148:149], v[72:73]
	s_cmp_lg_u32 s22, s35
	s_cbranch_scc1 .LBB0_357
	v_cndmask_b32_e64 v4, v84, v245, s[48:49]
	v_cndmask_b32_e64 v100, v100, v245, s[50:51]
	v_cndmask_b32_e64 v85, v245, v85, s[52:53]
	v_cndmask_b32_e64 v84, v4, v84, s[52:53]
	v_cndmask_b32_e64 v101, v101, v245, s[54:55]
	v_cndmask_b32_e64 v86, v86, v245, s[56:57]
	v_cndmask_b32_e64 v102, v102, v245, s[58:59]
	v_cndmask_b32_e64 v87, v87, v245, s[60:61]
	v_cndmask_b32_e64 v103, v103, v245, s[62:63]
	v_cndmask_b32_e64 v88, v88, v245, s[64:65]
	v_cndmask_b32_e64 v104, v104, v245, s[66:67]
	v_cndmask_b32_e64 v89, v89, v245, s[68:69]
	v_cndmask_b32_e64 v105, v105, v245, s[70:71]
	v_cndmask_b32_e64 v90, v90, v245, s[72:73]
	v_cndmask_b32_e64 v106, v106, v245, s[74:75]
	v_cndmask_b32_e64 v91, v91, v245, s[76:77]
	v_cndmask_b32_e64 v107, v107, v245, s[78:79]
	v_cndmask_b32_e64 v92, v92, v245, s[80:81]
	v_cndmask_b32_e64 v108, v108, v245, s[82:83]
	v_cndmask_b32_e64 v93, v93, v245, s[84:85]
	v_cndmask_b32_e64 v109, v109, v245, s[86:87]
	v_cndmask_b32_e64 v94, v94, v245, s[88:89]
	v_cndmask_b32_e64 v110, v110, v245, s[90:91]
	v_cndmask_b32_e64 v95, v95, v245, s[92:93]
	v_cndmask_b32_e64 v111, v111, v245, s[94:95]
	v_cndmask_b32_e64 v96, v96, v245, s[96:97]
	v_cndmask_b32_e64 v112, v112, v245, s[4:5]
	v_cndmask_b32_e64 v97, v97, v245, s[6:7]
	v_cndmask_b32_e64 v113, v113, v245, s[8:9]
	v_cndmask_b32_e64 v98, v98, v245, s[10:11]
	v_cndmask_b32_e64 v114, v114, v245, s[12:13]
	v_cndmask_b32_e64 v99, v99, v245, s[14:15]
	v_cndmask_b32_e64 v115, v115, v245, s[16:17]
; template <int KIND> DI void attn_unit(const Params& P, int b, int h, int qb, char* shm, float lam, bool dry = false) {
;     ...
;         ATT_FIX(pb0, pb1, ATT_TILE(i + 1));
;         float rm, rm2;
;         if (NDB == 4) {
;             LDV(11); PVM(8); rm = max3f(pb0[0], pb0[1], pb1[0]); rm2 = max3f(pb0[2], pb0[3], pb1[1]); PIN(rm); PIN(rm2); SBAR();
;             LDV(12); PVM(9); rm = max3f(rm, pb1[2], pb1[3]); rm2 = max3f(rm2, pb0[4], pb0[5]); PIN(rm); PIN(rm2); SBAR();
;             LDV(13); PVM(10); rm = max3f(rm, pb0[6], pb0[7]); rm2 = max3f(rm2, pb1[4], pb1[5]); PIN(rm); PIN(rm2); SBAR();
;             LDV(14); PVM(11); rm = max3f(rm, pb1[6], pb1[7]); rm2 = max3f(rm2, pb0[8], pb0[9]); PIN(rm); PIN(rm2); SBAR();
;             LDV(15); PVM(12); rm = max3f(rm, pb0[10], pb0[11]); rm2 = max3f(rm2, pb1[8], pb1[9]); PIN(rm); PIN(rm2); SBAR();
;             PVM(13); rm = max3f(rm, pb1[10], pb1[11]); rm2 = max3f(rm2, pb0[12], pb0[13]); PIN(rm); PIN(rm2); SBAR();
;             PVM(14); rm = max3f(rm, pb0[14], pb0[15]); rm2 = max3f(rm2, pb1[12], pb1[13]); PIN(rm); PIN(rm2); SBAR();
;             PVM(15); rm = max3f(rm, pb1[14], pb1[15]); PIN(rm); SBAR();
;         } else {
;             LDV(7); PVM(4); rm = max3f(pb0[0], pb0[1], pb1[0]); rm2 = max3f(pb0[2], pb0[3], pb1[1]); rm = max3f(rm, pb1[2], pb1[3]); rm2 = max3f(rm2, pb0[4], pb0[5]); PIN(rm); PIN(rm2); SBAR();
;             PVM(5); rm = max3f(rm, pb0[6], pb0[7]); rm2 = max3f(rm2, pb1[4], pb1[5]); rm = max3f(rm, pb1[6], pb1[7]); rm2 = max3f(rm2, pb0[8], pb0[9]); PIN(rm); PIN(rm2); SBAR();
;             PVM(6); rm = max3f(rm, pb0[10], pb0[11]); rm2 = max3f(rm2, pb1[8], pb1[9]); rm = max3f(rm, pb1[10], pb1[11]); rm2 = max3f(rm2, pb0[12], pb0[13]); PIN(rm); PIN(rm2); SBAR();
;             PVM(7); rm = max3f(rm, pb0[14], pb0[15]); rm2 = max3f(rm2, pb1[12], pb1[13]); rm = max3f(rm, pb1[14], pb1[15]); PIN(rm); PIN(rm2); SBAR();
;         }
;     ...
;         rm = swapmax(max3f(rm, rm2, rm2));
;         if (KIND == 2) {
;             const u32x2 kx = *(const LAS u32x2*)(shm3 + sc + 32768);
;             const float xk0 = __uint_as_float(kx.x << 16) + __uint_as_float(kx.x & 0xffff0000u) + __uint_as_float(kx.y << 16);
;             const float ltot = swapsum(lsum);
;             const bool ok = (qkmax + cb + xk0) < (mhat + __builtin_amdgcn_logf(ltot) - 54.0f);
;             const bool allok = __all(ok) && !(ATT_TILE(i) > wt_hi);
.LBB0_357:
	s_add_i32 s19, s20, 2
	s_cmp_lt_i32 s19, 0
	s_cselect_b64 s[38:39], -1, 0
	s_cmp_gt_i32 s19, s36
	s_waitcnt lgkmcnt(4)
	v_mfma_f32_32x32x16_bf16 v[52:67], v[116:119], v[152:155], v[52:67]
	s_cselect_b64 vcc, -1, 0
	s_or_b64 vcc, s[38:39], vcc
	s_cbranch_vccz .Lct1_nomask
	v_mov_b32_e32 v84, v245
	v_mov_b32_e32 v85, v245
	v_mov_b32_e32 v86, v245
	v_mov_b32_e32 v87, v245
	v_mov_b32_e32 v88, v245
	v_mov_b32_e32 v89, v245
	v_mov_b32_e32 v90, v245
	v_mov_b32_e32 v91, v245
	v_mov_b32_e32 v92, v245
	v_mov_b32_e32 v93, v245
	v_mov_b32_e32 v94, v245
	v_mov_b32_e32 v95, v245
	v_mov_b32_e32 v96, v245
	v_mov_b32_e32 v97, v245
	v_mov_b32_e32 v98, v245
	v_mov_b32_e32 v99, v245
	v_mov_b32_e32 v100, v245
	v_mov_b32_e32 v101, v245
	v_mov_b32_e32 v102, v245
	v_mov_b32_e32 v103, v245
	v_mov_b32_e32 v104, v245
	v_mov_b32_e32 v105, v245
	v_mov_b32_e32 v106, v245
	v_mov_b32_e32 v107, v245
	v_mov_b32_e32 v108, v245
	v_mov_b32_e32 v109, v245
	v_mov_b32_e32 v110, v245
	v_mov_b32_e32 v111, v245
	v_mov_b32_e32 v112, v245
	v_mov_b32_e32 v113, v245
	v_mov_b32_e32 v114, v245
	v_mov_b32_e32 v115, v245
.Lct1_nomask:
	v_add_f32_e32 v169, v169, v68
	ds_read_b64_tr_b16 v[128:129], v164 offset:23552
	ds_read_b64_tr_b16 v[130:131], v164 offset:24064
	v_max3_f32 v116, v84, v85, v100
	v_max3_f32 v117, v86, v87, v101
	v_max3_f32 v116, v116, v102, v103
	v_max3_f32 v117, v117, v88, v89
	s_nop 0
	s_waitcnt lgkmcnt(4)
	v_mfma_f32_32x32x16_bf16 v[36:51], v[120:123], v[152:155], v[36:51]
	v_max3_f32 v116, v116, v90, v91
	v_max3_f32 v117, v117, v104, v105
	s_nop 0
	v_max3_f32 v116, v116, v106, v107
	v_max3_f32 v117, v117, v92, v93
	s_nop 0
	s_waitcnt lgkmcnt(2)
	v_mfma_f32_32x32x16_bf16 v[52:67], v[124:127], v[148:151], v[52:67]
	v_max3_f32 v116, v116, v94, v95
	v_max3_f32 v117, v117, v108, v109
	s_nop 0
	v_max3_f32 v116, v116, v110, v111
	v_max3_f32 v117, v117, v96, v97
	s_nop 0
	s_waitcnt lgkmcnt(0)
	v_mfma_f32_32x32x16_bf16 v[36:51], v[128:131], v[148:151], v[36:51]
	v_max3_f32 v116, v116, v98, v99
	v_max3_f32 v117, v117, v112, v113
	s_nop 0
	v_max3_f32 v116, v116, v114, v115
	s_nop 0
	v_mov_b32_e32 v118, s18
	ds_read_b64 v[118:119], v118 offset:32768
	v_max3_f32 v116, v116, v117, v117
	s_mov_b64 s[18:19], exec
	v_mov_b32_e32 v117, v116
	s_nop 1
	v_permlane32_swap_b32_e32 v116, v117
	s_waitcnt lgkmcnt(0)
	v_lshlrev_b32_e32 v120, 16, v118
	v_and_b32_e32 v118, 0xffff0000, v118
	v_add_f32_e32 v164, v120, v118
	v_lshlrev_b32_e32 v118, 16, v119
	v_mov_b32_e32 v119, v169
	v_mov_b32_e32 v120, v169
	s_nop 1
	v_permlane32_swap_b32_e32 v119, v120
	v_add_f32_e32 v119, v119, v120
	v_log_f32_e32 v119, v119
	s_nop 0
	v_pk_add_f32 v[118:119], v[164:165], v[118:119]
	s_nop 0
	v_pk_add_f32 v[118:119], v[202:203], v[118:119]
	s_nop 0
	v_cmp_lt_f32_e32 vcc, v118, v119
	s_and_saveexec_b64 s[38:39], s[46:47]
	s_cbranch_execz .LBB0_359
	s_sub_i32 s26, s25, 24
	s_and_b32 s26, s26, 24
	s_lshl_b32 s26, s26, 2
	s_add_i32 s34, s37, s26
	s_cmp_eq_u64 vcc, s[18:19]
	s_cselect_b64 s[18:19], -1, 0
	s_cmp_ge_i32 s35, s40
	s_cselect_b64 s[26:27], -1, 0
	s_and_b64 s[18:19], s[18:19], s[26:27]
	v_cndmask_b32_e64 v118, 0, 1, s[18:19]
	v_mov_b32_e32 v119, s34
	ds_write_b32 v119, v118
.LBB0_359:
	s_or_b64 exec, exec, s[38:39]
	v_cmp_ge_i32_e64 s[18:19], s31, v173
	s_and_b64 vcc, exec, s[18:19]
	s_cbranch_vccnz .LBB0_362
	v_max_f32_e32 v116, v116, v116
	v_max_f32_e32 v117, v117, v117
	v_max_f32_e32 v116, v116, v117
	v_cmp_lt_f32_e32 vcc, s3, v116
	s_cbranch_vccz .LBB0_362
	v_max_f32_e32 v116, v116, v116
	v_max_f32_e32 v117, 0, v116
	v_exp_f32_e64 v116, -v117
	v_add_f32_e32 v165, v165, v117
	v_sub_f32_e32 v99, v99, v117
	v_sub_f32_e32 v98, v98, v117
	v_pk_mul_f32 v[50:51], v[50:51], v[116:117] op_sel_hi:[1,0]
	v_pk_mul_f32 v[48:49], v[48:49], v[116:117] op_sel_hi:[1,0]
	v_pk_mul_f32 v[46:47], v[46:47], v[116:117] op_sel_hi:[1,0]
	v_pk_mul_f32 v[44:45], v[44:45], v[116:117] op_sel_hi:[1,0]
	v_pk_mul_f32 v[42:43], v[42:43], v[116:117] op_sel_hi:[1,0]
	v_pk_mul_f32 v[40:41], v[40:41], v[116:117] op_sel_hi:[1,0]
	v_pk_mul_f32 v[38:39], v[38:39], v[116:117] op_sel_hi:[1,0]
	v_pk_mul_f32 v[36:37], v[36:37], v[116:117] op_sel_hi:[1,0]
	v_pk_mul_f32 v[66:67], v[66:67], v[116:117] op_sel_hi:[1,0]
	v_pk_mul_f32 v[64:65], v[64:65], v[116:117] op_sel_hi:[1,0]
	v_pk_mul_f32 v[62:63], v[62:63], v[116:117] op_sel_hi:[1,0]
	v_pk_mul_f32 v[60:61], v[60:61], v[116:117] op_sel_hi:[1,0]
	v_pk_mul_f32 v[58:59], v[58:59], v[116:117] op_sel_hi:[1,0]
	v_pk_mul_f32 v[56:57], v[56:57], v[116:117] op_sel_hi:[1,0]
	v_pk_mul_f32 v[54:55], v[54:55], v[116:117] op_sel_hi:[1,0]
	v_pk_mul_f32 v[52:53], v[52:53], v[116:117] op_sel_hi:[1,0]
	v_sub_f32_e32 v97, v97, v117
	v_sub_f32_e32 v96, v96, v117
	v_sub_f32_e32 v95, v95, v117
	v_sub_f32_e32 v94, v94, v117
	v_sub_f32_e32 v93, v93, v117
	v_sub_f32_e32 v92, v92, v117
	v_sub_f32_e32 v91, v91, v117
	v_sub_f32_e32 v90, v90, v117
	v_sub_f32_e32 v89, v89, v117
	v_sub_f32_e32 v88, v88, v117
	v_sub_f32_e32 v87, v87, v117
	v_sub_f32_e32 v86, v86, v117
	v_sub_f32_e32 v85, v85, v117
	v_sub_f32_e32 v84, v84, v117
	v_sub_f32_e32 v115, v115, v117
	v_sub_f32_e32 v114, v114, v117
	v_sub_f32_e32 v113, v113, v117
	v_sub_f32_e32 v112, v112, v117
	v_sub_f32_e32 v111, v111, v117
	v_sub_f32_e32 v110, v110, v117
	v_sub_f32_e32 v109, v109, v117
	v_sub_f32_e32 v108, v108, v117
	v_sub_f32_e32 v107, v107, v117
	v_sub_f32_e32 v106, v106, v117
	v_sub_f32_e32 v105, v105, v117
	v_sub_f32_e32 v104, v104, v117
	v_sub_f32_e32 v103, v103, v117
	v_sub_f32_e32 v102, v102, v117
	v_sub_f32_e32 v101, v101, v117
	v_sub_f32_e32 v100, v100, v117
	v_sub_f32_e32 v35, v35, v117
	v_sub_f32_e32 v34, v34, v117
	v_sub_f32_e32 v33, v33, v117
	v_sub_f32_e32 v32, v32, v117
	v_sub_f32_e32 v31, v31, v117
	v_sub_f32_e32 v30, v30, v117
	v_sub_f32_e32 v29, v29, v117
	v_sub_f32_e32 v28, v28, v117
	v_sub_f32_e32 v27, v27, v117
	v_sub_f32_e32 v26, v26, v117
	v_sub_f32_e32 v25, v25, v117
	v_sub_f32_e32 v24, v24, v117
	v_sub_f32_e32 v23, v23, v117
	v_sub_f32_e32 v22, v22, v117
	v_sub_f32_e32 v21, v21, v117
	v_sub_f32_e32 v20, v20, v117
	v_mul_f32_e32 v169, v169, v116
.LBB0_362:
	s_add_i32 s26, s30, 0x8400
	s_cmp_lg_u32 s30, 0x18c00
	s_cselect_b32 s30, s26, 0
	s_add_i32 s25, s25, 8
	s_andn2_b64 vcc, exec, s[18:19]
	s_add_i32 s20, s20, -1
	s_cbranch_vccz .LBB0_364
	s_mov_b32 s35, s31
	s_mov_b32 s34, s29
	s_branch .Lct2_341
.Lct2_341:
	s_cmp_eq_u32 s35, 0
	s_cselect_b64 s[18:19], -1, 0
	s_cmp_lg_u32 s35, 0
	s_cselect_b64 s[38:39], -1, 0
	s_cmp_lt_u32 s35, s24
	s_cselect_b64 vcc, -1, 0
	s_and_b64 s[38:39], s[38:39], vcc
	s_andn2_b64 vcc, exec, s[38:39]
	s_mov_b64 s[38:39], -1
	s_cbranch_vccz .Lct2_343
	s_waitcnt vmcnt(0) lgkmcnt(0)
	s_barrier
	s_mov_b64 s[38:39], 0

.Lct2_348:
	s_cmp_gt_u32 s35, s33
	s_cbranch_scc1 .Lct2_351
	s_lshl_b64 s[38:39], s[20:21], 13
	v_lshl_add_u64 v[116:117], v[156:157], 0, s[38:39]
	s_add_i32 s26, s41, s30
	s_mov_b32 s27, m0
	s_mov_b32 m0, s26
	s_nop 0
	global_load_lds_dwordx4 v[116:117], off
	s_mov_b32 m0, s27
	s_lshl_b64 s[38:39], s[20:21], 12
	v_lshl_add_u64 v[116:117], v[158:159], 0, s[38:39]
	s_add_i32 s26, s23, s30
	s_mov_b32 s27, m0
	s_mov_b32 m0, s26
	s_nop 0
	global_load_lds_dwordx4 v[116:117], off
	s_mov_b32 m0, s27
	s_and_b64 vcc, exec, s[42:43]
	s_cbranch_vccnz .Lct2_351
	s_lshl_b64 s[38:39], s[20:21], 10
	s_cmp_lg_u32 0, -1
	s_cselect_b32 s26, 0, 0
	s_add_i32 s26, s26, s30
	v_lshl_add_u64 v[116:117], v[160:161], 0, s[38:39]
	s_add_i32 s26, s26, 0x8000
	s_mov_b32 s27, m0
	s_mov_b32 m0, s26
	s_nop 0
	global_load_lds_dwordx4 v[116:117], off
	s_mov_b32 m0, s27

; #define SBAR() __builtin_amdgcn_sched_barrier(0)
; template <int KIND> DI void attn_unit(const Params& P, int b, int h, int qb, char* shm, float lam, bool dry = false) {
;     ...
;         const int sn = (sc == 3 * SLOT) ? 0 : sc + SLOT;
;         const lds_cptr vp = shm3 + sc + 16384 + vlane;
;         bf16x8 vq[4]; bf16x8 pw[4]; u32x4 w0, w1; float sacc = 0.f;
;     ...
;         ATT_KLD(sn, 0); ATT_XLD(sn);
;         SBAR();
;     ...
;         G1(pb0 = MF(kf[0], qr[0], negm), 0, w0, 0);  G1(pb1 = MF(kf[1], qr[0], negm), 2, w0, 1);
;         G1(pb0 = MF(kf[2], qr[1], pb0), 4, w0, 2);   G1(pb1 = MF(kf[3], qr[1], pb1), 6, w0, 3);
;         ATT_KLD(sn, 1);
;         SBAR();
;         G1(pb0 = MF(kf[0], qr[2], pb0), 8, w1, 0);   G1(pb1 = MF(kf[1], qr[2], pb1), 10, w1, 1);
;         LDV(0); SBAR();
;         G1(pb0 = MF(kf[2], qr[3], pb0), 12, w1, 2);
;         LDV(1); SBAR();
;         G1(pb1 = MF(kf[3], qr[3], pb1), 14, w1, 3);
;         LDV(2); SBAR();
;     ...
;         if (KIND == 2) { pb0 = MF(x0, ones, pb0); pb1 = MF(x1, ones, pb1); }
;         pw[0] = __builtin_bit_cast(bf16x8, w0); pw[1] = __builtin_bit_cast(bf16x8, w1);
;     ...
;         if (NDB == 4) {
;             LDV(3); PVM(0); E4(0, w0, 0); PIN(pa1); PIN(sacc); PIN(w0); SBAR();
;             LDV(4); PVM(1); E4(2, w0, 1); PIN(pa1); PIN(sacc); PIN(w0); SBAR();
;             LDV(5); PVM(2); E4(4, w0, 2); PIN(pa1); PIN(sacc); PIN(w0); SBAR();
;             LDV(6); PVM(3); E4(6, w0, 3); PIN(pa1); PIN(sacc); PIN(w0); SBAR();
;             LDV(7); PVM(4); E4(8, w1, 0); PIN(pa1); PIN(sacc); PIN(w1); SBAR();
;             LDV(8); PVM(5); E4(10, w1, 1); PIN(pa1); PIN(sacc); PIN(w1); SBAR();
;             LDV(9); PVM(6); E4(12, w1, 2); PIN(pa1); PIN(sacc); PIN(w1); SBAR();
;             LDV(10); PVM(7); E4(14, w1, 3); PIN(pa1); PIN(sacc); PIN(w1); SBAR();
;         } else {
;             LDV(3); PVM(0); E4(0, w0, 0); E4(2, w0, 1); PIN(pa1); PIN(sacc); PIN(w0); SBAR();
;             LDV(4); PVM(1); E4(4, w0, 2); E4(6, w0, 3); PIN(pa1); PIN(sacc); PIN(w0); SBAR();
;             LDV(5); PVM(2); E4(8, w1, 0); E4(10, w1, 1); PIN(pa1); PIN(sacc); PIN(w1); SBAR();
;             LDV(6); PVM(3); E4(12, w1, 2); E4(14, w1, 3); PIN(pa1); PIN(sacc); PIN(w1); SBAR();
;         }
;     ...
;         pw[2] = __builtin_bit_cast(bf16x8, w0); pw[3] = __builtin_bit_cast(bf16x8, w1);
;         lsum += sacc;
;         ATT_FIX(pb0, pb1, ATT_TILE(i + 1));
.Lct2_353:
	s_andn2_b64 vcc, exec, s[18:19]
	s_cbranch_vccnz .Lct2_355
	s_and_b32 s18, s25, 24
	s_lshl_b32 s18, s18, 2
	s_add_i32 s18, s18, 0
	s_add_i32 s18, s18, 0x23240
	v_mov_b32_e32 v120, s18
	ds_read_b128 v[116:119], v120
	ds_read_b128 v[120:123], v120 offset:16
	s_add_i32 s31, s35, 1
	s_waitcnt lgkmcnt(1)
	v_and_b32_e32 v116, v116, v117
	v_and_b32_e32 v116, v116, v118
	v_and_b32_e32 v116, v116, v119
	s_waitcnt lgkmcnt(0)
	v_and_b32_e32 v116, v116, v120
	v_and_b32_e32 v116, v116, v121
	v_and_b32_e32 v116, v116, v122
	v_and_b32_e32 v116, v116, v123
	v_cmp_eq_u32_e32 vcc, 0, v116
	v_mov_b32_e32 v116, s31
	s_nop 0
	v_cndmask_b32_e32 v173, v116, v173, vcc
.Lct2_355:
	s_add_i32 s18, s34, 0x8400
	s_cmp_lg_u32 s34, 0x18c00
	s_cselect_b32 s29, s18, 0
	s_add_i32 s18, s29, 0
	v_add_u32_e32 v116, s18, v168
	v_add_u32_e32 v186, v116, v167
	ds_read_b128 v[4:7], v186
	ds_read_b128 v[174:177], v186 offset:512
	ds_read_b128 v[178:181], v186 offset:2048
	ds_read_b128 v[182:185], v186 offset:2560
	ds_read_b128 v[190:193], v116 offset:32768
	ds_read_b128 v[196:199], v116 offset:33280
	v_exp_f32_e32 v84, v84
	v_exp_f32_e32 v85, v85
	s_nop 0
	v_cvt_pk_bf16_f32 v152, v84, v85
	v_add_f32_e32 v116, 0, v84
	v_add_f32_e32 v116, v85, v116
	s_nop 0
	v_exp_f32_e32 v86, v86
	v_exp_f32_e32 v87, v87
	v_add_f32_e32 v116, v116, v86
	v_add_f32_e32 v116, v87, v116
	v_cvt_pk_bf16_f32 v153, v86, v87
	s_nop 0
	v_exp_f32_e32 v88, v88
	v_exp_f32_e32 v89, v89
	v_add_f32_e32 v116, v116, v88
	v_add_f32_e32 v187, v89, v116
	v_cvt_pk_bf16_f32 v154, v88, v89
	s_waitcnt lgkmcnt(5)
	v_mfma_f32_32x32x16_bf16 v[116:131], v[4:7], v[144:147], v[20:35]
	v_exp_f32_e32 v90, v90
	v_exp_f32_e32 v91, v91
	s_waitcnt lgkmcnt(4)
	v_mfma_f32_32x32x16_bf16 v[4:19], v[174:177], v[144:147], v[20:35]
	s_add_i32 s18, s34, 0
	v_exp_f32_e32 v92, v92
	v_exp_f32_e32 v93, v93
	s_waitcnt lgkmcnt(3)
	v_mfma_f32_32x32x16_bf16 v[116:131], v[178:181], v[140:143], v[116:131]
	v_add3_u32 v68, s18, v170, v171
	v_add_f32_e32 v72, v187, v90
	v_cvt_pk_bf16_f32 v148, v92, v93
	v_add_u32_e32 v164, v68, v172
	s_waitcnt lgkmcnt(0)
	v_add_f32_e32 v187, v91, v72
	v_cvt_pk_bf16_f32 v155, v90, v91
	v_mfma_f32_32x32x16_bf16 v[4:19], v[182:185], v[140:143], v[4:19]
	ds_read_b128 v[72:75], v186 offset:4096
	ds_read_b128 v[80:83], v186 offset:4608
	ds_read_b128 v[174:177], v186 offset:6144
	ds_read_b128 v[178:181], v186 offset:6656
	s_waitcnt lgkmcnt(3)
	v_mfma_f32_32x32x16_bf16 v[116:131], v[72:75], v[136:139], v[116:131]
	v_add_f32_e32 v72, v187, v92
	v_add_f32_e32 v72, v93, v72
	s_waitcnt lgkmcnt(2)
	v_mfma_f32_32x32x16_bf16 v[4:19], v[80:83], v[136:139], v[4:19]
	v_exp_f32_e32 v94, v94
	v_exp_f32_e32 v95, v95
	v_add_f32_e32 v72, v72, v94
	v_add_f32_e32 v80, v95, v72
	v_cvt_pk_bf16_f32 v149, v94, v95
	ds_read_b64_tr_b16 v[72:73], v164 offset:16384
	ds_read_b64_tr_b16 v[74:75], v164 offset:16896
	s_waitcnt lgkmcnt(3)
	v_mfma_f32_32x32x16_bf16 v[116:131], v[174:177], v[132:135], v[116:131]
	v_exp_f32_e32 v96, v96
	v_exp_f32_e32 v97, v97
	v_add_f32_e32 v80, v80, v96
	v_add_f32_e32 v174, v97, v80
	v_cvt_pk_bf16_f32 v150, v96, v97
	ds_read_b64_tr_b16 v[80:81], v164 offset:20480
	ds_read_b64_tr_b16 v[82:83], v164 offset:20992
	s_waitcnt lgkmcnt(4)
	v_mfma_f32_32x32x16_bf16 v[4:19], v[178:181], v[132:135], v[4:19]
	v_exp_f32_e32 v98, v98
	v_exp_f32_e32 v99, v99
	v_add_f32_e32 v151, v174, v98
	v_add_f32_e32 v174, v99, v151
	v_cvt_pk_bf16_f32 v151, v98, v99
	ds_read_b64_tr_b16 v[92:93], v164 offset:17408
	ds_read_b64_tr_b16 v[94:95], v164 offset:17920
	v_mfma_f32_32x32x16_bf16 v[116:131], v[190:193], v[0:3], v[116:131]
	v_exp_f32_e32 v100, v100
	v_exp_f32_e32 v101, v101
	v_exp_f32_e32 v102, v102
	v_exp_f32_e32 v103, v103
	v_cvt_pk_bf16_f32 v77, v100, v101
	v_mfma_f32_32x32x16_bf16 v[4:19], v[196:199], v[0:3], v[4:19]
	ds_read_b64_tr_b16 v[68:69], v164 offset:21504
	ds_read_b64_tr_b16 v[70:71], v164 offset:22016
	s_waitcnt lgkmcnt(6)
	v_mfma_f32_32x32x16_bf16 v[52:67], v[72:75], v[152:155], v[52:67]
	v_add_f32_e32 v72, v100, v174
	v_add_f32_e32 v76, v101, v72
	v_mov_b64_e32 v[72:73], v[152:153]
	v_add_f32_e32 v73, v102, v76
	v_mov_b64_e32 v[74:75], v[154:155]
	v_mov_b32_e32 v72, v77
	v_add_f32_e32 v76, v103, v73
	v_cvt_pk_bf16_f32 v73, v102, v103
	s_nop 0
	v_exp_f32_e32 v104, v104
	v_exp_f32_e32 v105, v105
	s_waitcnt lgkmcnt(4)
	v_mfma_f32_32x32x16_bf16 v[36:51], v[80:83], v[152:155], v[36:51]
	v_exp_f32_e32 v106, v106
	v_exp_f32_e32 v107, v107
	v_add_f32_e32 v74, v76, v104
	ds_read_b64_tr_b16 v[84:85], v164 offset:18432
	ds_read_b64_tr_b16 v[86:87], v164 offset:18944
	v_add_f32_e32 v75, v105, v74
	v_add_f32_e32 v75, v106, v75
	v_cvt_pk_bf16_f32 v74, v104, v105
	v_add_f32_e32 v76, v107, v75
	v_cvt_pk_bf16_f32 v75, v106, v107
	v_mov_b64_e32 v[154:155], v[74:75]
	v_mov_b64_e32 v[152:153], v[72:73]
	s_nop 0
	v_exp_f32_e32 v108, v108
	s_waitcnt lgkmcnt(4)
	v_mfma_f32_32x32x16_bf16 v[52:67], v[92:95], v[148:151], v[52:67]
	v_exp_f32_e32 v109, v109
	v_exp_f32_e32 v110, v110
	ds_read_b64_tr_b16 v[88:89], v164 offset:22528
	ds_read_b64_tr_b16 v[90:91], v164 offset:23040
	v_exp_f32_e32 v111, v111
	v_add_f32_e32 v72, v76, v108
	v_add_f32_e32 v76, v109, v72
	v_mov_b64_e32 v[72:73], v[148:149]
	v_cvt_pk_bf16_f32 v77, v108, v109
	v_add_f32_e32 v73, v110, v76
	v_mov_b64_e32 v[74:75], v[150:151]
	v_mov_b32_e32 v72, v77
	v_add_f32_e32 v76, v111, v73
	v_cvt_pk_bf16_f32 v73, v110, v111
	s_waitcnt lgkmcnt(4)
	v_mfma_f32_32x32x16_bf16 v[36:51], v[68:71], v[148:151], v[36:51]
	v_exp_f32_e32 v112, v112
	v_exp_f32_e32 v113, v113
	v_exp_f32_e32 v114, v114
	v_exp_f32_e32 v115, v115
	ds_read_b64_tr_b16 v[92:93], v164 offset:19456
	ds_read_b64_tr_b16 v[94:95], v164 offset:19968
	v_add_f32_e32 v68, v76, v112
	v_add_f32_e32 v68, v113, v68
	v_cvt_pk_bf16_f32 v74, v112, v113
	v_cvt_pk_bf16_f32 v75, v114, v115
	v_add_f32_e32 v68, v114, v68
	v_mov_b64_e32 v[150:151], v[74:75]
	v_add_f32_e32 v68, v115, v68
	v_mov_b64_e32 v[148:149], v[72:73]
	s_cmp_lg_u32 s22, s35
	s_cbranch_scc1 .Lct2_357
; template <int KIND> DI void attn_unit(const Params& P, int b, int h, int qb, char* shm, float lam, bool dry = false) {
;     ...
;         ATT_FIX(pb0, pb1, ATT_TILE(i + 1));
;         float rm, rm2;
;         if (NDB == 4) {
;             LDV(11); PVM(8); rm = max3f(pb0[0], pb0[1], pb1[0]); rm2 = max3f(pb0[2], pb0[3], pb1[1]); PIN(rm); PIN(rm2); SBAR();
;             LDV(12); PVM(9); rm = max3f(rm, pb1[2], pb1[3]); rm2 = max3f(rm2, pb0[4], pb0[5]); PIN(rm); PIN(rm2); SBAR();
;             LDV(13); PVM(10); rm = max3f(rm, pb0[6], pb0[7]); rm2 = max3f(rm2, pb1[4], pb1[5]); PIN(rm); PIN(rm2); SBAR();
;             LDV(14); PVM(11); rm = max3f(rm, pb1[6], pb1[7]); rm2 = max3f(rm2, pb0[8], pb0[9]); PIN(rm); PIN(rm2); SBAR();
;             LDV(15); PVM(12); rm = max3f(rm, pb0[10], pb0[11]); rm2 = max3f(rm2, pb1[8], pb1[9]); PIN(rm); PIN(rm2); SBAR();
;             PVM(13); rm = max3f(rm, pb1[10], pb1[11]); rm2 = max3f(rm2, pb0[12], pb0[13]); PIN(rm); PIN(rm2); SBAR();
;             PVM(14); rm = max3f(rm, pb0[14], pb0[15]); rm2 = max3f(rm2, pb1[12], pb1[13]); PIN(rm); PIN(rm2); SBAR();
;             PVM(15); rm = max3f(rm, pb1[14], pb1[15]); PIN(rm); SBAR();
;         } else {
;             LDV(7); PVM(4); rm = max3f(pb0[0], pb0[1], pb1[0]); rm2 = max3f(pb0[2], pb0[3], pb1[1]); rm = max3f(rm, pb1[2], pb1[3]); rm2 = max3f(rm2, pb0[4], pb0[5]); PIN(rm); PIN(rm2); SBAR();
;             PVM(5); rm = max3f(rm, pb0[6], pb0[7]); rm2 = max3f(rm2, pb1[4], pb1[5]); rm = max3f(rm, pb1[6], pb1[7]); rm2 = max3f(rm2, pb0[8], pb0[9]); PIN(rm); PIN(rm2); SBAR();
;             PVM(6); rm = max3f(rm, pb0[10], pb0[11]); rm2 = max3f(rm2, pb1[8], pb1[9]); rm = max3f(rm, pb1[10], pb1[11]); rm2 = max3f(rm2, pb0[12], pb0[13]); PIN(rm); PIN(rm2); SBAR();
;             PVM(7); rm = max3f(rm, pb0[14], pb0[15]); rm2 = max3f(rm2, pb1[12], pb1[13]); rm = max3f(rm, pb1[14], pb1[15]); PIN(rm); PIN(rm2); SBAR();
;         }
;     ...
;         rm = swapmax(max3f(rm, rm2, rm2));
;         if (KIND == 2) {
;             const u32x2 kx = *(const LAS u32x2*)(shm3 + sc + 32768);
;             const float xk0 = __uint_as_float(kx.x << 16) + __uint_as_float(kx.x & 0xffff0000u) + __uint_as_float(kx.y << 16);
;             const float ltot = swapsum(lsum);
;             const bool ok = (qkmax + cb + xk0) < (mhat + __builtin_amdgcn_logf(ltot) - 54.0f);
;             const bool allok = __all(ok) && !(ATT_TILE(i) > wt_hi);
	v_cndmask_b32_e64 v100, v116, v245, s[48:49]
	v_cndmask_b32_e64 v4, v4, v245, s[50:51]
	v_cndmask_b32_e64 v117, v245, v117, s[52:53]
	v_cndmask_b32_e64 v116, v100, v116, s[52:53]
	v_cndmask_b32_e64 v5, v5, v245, s[54:55]
	v_cndmask_b32_e64 v118, v118, v245, s[56:57]
	v_cndmask_b32_e64 v6, v6, v245, s[58:59]
	v_cndmask_b32_e64 v119, v119, v245, s[60:61]
	v_cndmask_b32_e64 v7, v7, v245, s[62:63]
	v_cndmask_b32_e64 v120, v120, v245, s[64:65]
	v_cndmask_b32_e64 v8, v8, v245, s[66:67]
	v_cndmask_b32_e64 v121, v121, v245, s[68:69]
	v_cndmask_b32_e64 v9, v9, v245, s[70:71]
	v_cndmask_b32_e64 v122, v122, v245, s[72:73]
	v_cndmask_b32_e64 v10, v10, v245, s[74:75]
	v_cndmask_b32_e64 v123, v123, v245, s[76:77]
	v_cndmask_b32_e64 v11, v11, v245, s[78:79]
	v_cndmask_b32_e64 v124, v124, v245, s[80:81]
	v_cndmask_b32_e64 v12, v12, v245, s[82:83]
	v_cndmask_b32_e64 v125, v125, v245, s[84:85]
	v_cndmask_b32_e64 v13, v13, v245, s[86:87]
	v_cndmask_b32_e64 v126, v126, v245, s[88:89]
	v_cndmask_b32_e64 v14, v14, v245, s[90:91]
	v_cndmask_b32_e64 v127, v127, v245, s[92:93]
	v_cndmask_b32_e64 v15, v15, v245, s[94:95]
	v_cndmask_b32_e64 v128, v128, v245, s[96:97]
	v_cndmask_b32_e64 v16, v16, v245, s[4:5]
	v_cndmask_b32_e64 v129, v129, v245, s[6:7]
	v_cndmask_b32_e64 v17, v17, v245, s[8:9]
	v_cndmask_b32_e64 v130, v130, v245, s[10:11]
	v_cndmask_b32_e64 v18, v18, v245, s[12:13]
	v_cndmask_b32_e64 v131, v131, v245, s[14:15]
	v_cndmask_b32_e64 v19, v19, v245, s[16:17]
.Lct2_357:
	s_add_i32 s19, s20, 2
	s_cmp_lt_i32 s19, 0
	s_cselect_b64 s[38:39], -1, 0
	s_cmp_gt_i32 s19, s36
	s_waitcnt lgkmcnt(4)
	v_mfma_f32_32x32x16_bf16 v[52:67], v[84:87], v[152:155], v[52:67]
	s_cselect_b64 vcc, -1, 0
	s_or_b64 vcc, s[38:39], vcc
	s_cbranch_vccz .Lct2x_nomask
	v_mov_b32_e32 v116, v245
	v_mov_b32_e32 v117, v245
	v_mov_b32_e32 v118, v245
	v_mov_b32_e32 v119, v245
	v_mov_b32_e32 v120, v245
	v_mov_b32_e32 v121, v245
	v_mov_b32_e32 v122, v245
	v_mov_b32_e32 v123, v245
	v_mov_b32_e32 v124, v245
	v_mov_b32_e32 v125, v245
	v_mov_b32_e32 v126, v245
	v_mov_b32_e32 v127, v245
	v_mov_b32_e32 v128, v245
	v_mov_b32_e32 v129, v245
	v_mov_b32_e32 v130, v245
	v_mov_b32_e32 v131, v245
	v_mov_b32_e32 v4, v245
	v_mov_b32_e32 v5, v245
	v_mov_b32_e32 v6, v245
	v_mov_b32_e32 v7, v245
	v_mov_b32_e32 v8, v245
	v_mov_b32_e32 v9, v245
	v_mov_b32_e32 v10, v245
	v_mov_b32_e32 v11, v245
	v_mov_b32_e32 v12, v245
	v_mov_b32_e32 v13, v245
	v_mov_b32_e32 v14, v245
	v_mov_b32_e32 v15, v245
	v_mov_b32_e32 v16, v245
	v_mov_b32_e32 v17, v245
	v_mov_b32_e32 v18, v245
	v_mov_b32_e32 v19, v245
.Lct2x_nomask:
	v_add_f32_e32 v169, v169, v68
	ds_read_b64_tr_b16 v[96:97], v164 offset:23552
	ds_read_b64_tr_b16 v[98:99], v164 offset:24064
	v_max3_f32 v84, v116, v117, v4
	v_max3_f32 v85, v118, v119, v5
	v_max3_f32 v84, v84, v6, v7
	v_max3_f32 v85, v85, v120, v121
	s_nop 0
	s_waitcnt lgkmcnt(4)
	v_mfma_f32_32x32x16_bf16 v[36:51], v[88:91], v[152:155], v[36:51]
	v_max3_f32 v84, v84, v122, v123
	v_max3_f32 v85, v85, v8, v9
	s_nop 0
	v_max3_f32 v84, v84, v10, v11
	v_max3_f32 v85, v85, v124, v125
	s_nop 0
	s_waitcnt lgkmcnt(2)
	v_mfma_f32_32x32x16_bf16 v[52:67], v[92:95], v[148:151], v[52:67]
	v_max3_f32 v84, v84, v126, v127
	v_max3_f32 v85, v85, v12, v13
	s_nop 0
	v_max3_f32 v84, v84, v14, v15
	v_max3_f32 v85, v85, v128, v129
	s_nop 0
	s_waitcnt lgkmcnt(0)
	v_mfma_f32_32x32x16_bf16 v[36:51], v[96:99], v[148:151], v[36:51]
	v_max3_f32 v84, v84, v130, v131
	v_max3_f32 v85, v85, v16, v17
	s_nop 0
	v_max3_f32 v84, v84, v18, v19
	s_nop 0
	v_mov_b32_e32 v86, s18
	ds_read_b64 v[86:87], v86 offset:32768
	v_max3_f32 v84, v84, v85, v85
	s_mov_b64 s[18:19], exec
	v_mov_b32_e32 v85, v84
	s_nop 1
	v_permlane32_swap_b32_e32 v84, v85
	s_waitcnt lgkmcnt(0)
	v_lshlrev_b32_e32 v88, 16, v86
	v_and_b32_e32 v86, 0xffff0000, v86
	v_add_f32_e32 v164, v88, v86
	v_lshlrev_b32_e32 v86, 16, v87
	v_mov_b32_e32 v87, v169
	v_mov_b32_e32 v88, v169
	s_nop 1
	v_permlane32_swap_b32_e32 v87, v88
	v_add_f32_e32 v87, v87, v88
	v_log_f32_e32 v87, v87
	s_nop 0
	v_pk_add_f32 v[86:87], v[164:165], v[86:87]
	s_nop 0
	v_pk_add_f32 v[86:87], v[202:203], v[86:87]
	s_nop 0
	v_cmp_lt_f32_e32 vcc, v86, v87
	s_and_saveexec_b64 s[38:39], s[46:47]
	s_cbranch_execz .Lct2_359
	s_sub_i32 s26, s25, 24
	s_and_b32 s26, s26, 24
	s_lshl_b32 s26, s26, 2
	s_add_i32 s34, s37, s26
	s_cmp_eq_u64 vcc, s[18:19]
	s_cselect_b64 s[18:19], -1, 0
	s_cmp_ge_i32 s35, s40
	s_cselect_b64 s[26:27], -1, 0
	s_and_b64 s[18:19], s[18:19], s[26:27]
	v_cndmask_b32_e64 v86, 0, 1, s[18:19]
	v_mov_b32_e32 v87, s34
	ds_write_b32 v87, v86
; #define ATT_DECIDE(P0, P1, rm_) do { if (__any((rm_) > 6.0f)) { const float dl = fmaxf((rm_), 0.f); mhat += dl; const float f = EX(-dl); lsum *= f; \
;             _Pragma("unroll") for (int r = 0; r < 16; ++r) { P0[r] -= dl; P1[r] -= dl; negm[r] -= dl; } \
;             _Pragma("unroll") for (int i2 = 0; i2 < NDB; ++i2) _Pragma("unroll") for (int r = 0; r < 16; ++r) o[i2][r] *= f; } } while (0)
; template <int KIND> DI void attn_unit(const Params& P, int b, int h, int qb, char* shm, float lam, bool dry = false) {
;     ...
;         if (i + 1 < nt_eff) ATT_DECIDE(pb0, pb1, rm);
.Lct2_359:
	s_or_b64 exec, exec, s[38:39]
	v_cmp_ge_i32_e64 s[18:19], s31, v173
	s_and_b64 vcc, exec, s[18:19]
	s_cbranch_vccnz .Lct2_362
	v_max_f32_e32 v84, v84, v84
	v_max_f32_e32 v85, v85, v85
	v_max_f32_e32 v84, v84, v85
	v_cmp_lt_f32_e32 vcc, s3, v84
	s_cbranch_vccz .Lct2_362
	v_max_f32_e32 v84, v84, v84
	v_max_f32_e32 v85, 0, v84
	v_exp_f32_e64 v84, -v85
	v_add_f32_e32 v165, v165, v85
	v_sub_f32_e32 v131, v131, v85
	v_sub_f32_e32 v130, v130, v85
	v_pk_mul_f32 v[50:51], v[50:51], v[84:85] op_sel_hi:[1,0]
	v_pk_mul_f32 v[48:49], v[48:49], v[84:85] op_sel_hi:[1,0]
	v_pk_mul_f32 v[46:47], v[46:47], v[84:85] op_sel_hi:[1,0]
	v_pk_mul_f32 v[44:45], v[44:45], v[84:85] op_sel_hi:[1,0]
	v_pk_mul_f32 v[42:43], v[42:43], v[84:85] op_sel_hi:[1,0]
	v_pk_mul_f32 v[40:41], v[40:41], v[84:85] op_sel_hi:[1,0]
	v_pk_mul_f32 v[38:39], v[38:39], v[84:85] op_sel_hi:[1,0]
	v_pk_mul_f32 v[36:37], v[36:37], v[84:85] op_sel_hi:[1,0]
	v_pk_mul_f32 v[66:67], v[66:67], v[84:85] op_sel_hi:[1,0]
	v_pk_mul_f32 v[64:65], v[64:65], v[84:85] op_sel_hi:[1,0]
	v_pk_mul_f32 v[62:63], v[62:63], v[84:85] op_sel_hi:[1,0]
	v_pk_mul_f32 v[60:61], v[60:61], v[84:85] op_sel_hi:[1,0]
	v_pk_mul_f32 v[58:59], v[58:59], v[84:85] op_sel_hi:[1,0]
	v_pk_mul_f32 v[56:57], v[56:57], v[84:85] op_sel_hi:[1,0]
	v_pk_mul_f32 v[54:55], v[54:55], v[84:85] op_sel_hi:[1,0]
	v_pk_mul_f32 v[52:53], v[52:53], v[84:85] op_sel_hi:[1,0]
	v_sub_f32_e32 v129, v129, v85
	v_sub_f32_e32 v128, v128, v85
	v_sub_f32_e32 v127, v127, v85
	v_sub_f32_e32 v126, v126, v85
	v_sub_f32_e32 v125, v125, v85
	v_sub_f32_e32 v124, v124, v85
	v_sub_f32_e32 v123, v123, v85
	v_sub_f32_e32 v122, v122, v85
	v_sub_f32_e32 v121, v121, v85
	v_sub_f32_e32 v120, v120, v85
	v_sub_f32_e32 v119, v119, v85
	v_sub_f32_e32 v118, v118, v85
	v_sub_f32_e32 v117, v117, v85
	v_sub_f32_e32 v116, v116, v85
	v_sub_f32_e32 v19, v19, v85
	v_sub_f32_e32 v18, v18, v85
	v_sub_f32_e32 v17, v17, v85
	v_sub_f32_e32 v16, v16, v85
	v_sub_f32_e32 v15, v15, v85
	v_sub_f32_e32 v14, v14, v85
	v_sub_f32_e32 v13, v13, v85
	v_sub_f32_e32 v12, v12, v85
	v_sub_f32_e32 v11, v11, v85
	v_sub_f32_e32 v10, v10, v85
	v_sub_f32_e32 v9, v9, v85
	v_sub_f32_e32 v8, v8, v85
	v_sub_f32_e32 v7, v7, v85
	v_sub_f32_e32 v6, v6, v85
	v_sub_f32_e32 v5, v5, v85
	v_sub_f32_e32 v4, v4, v85
	v_sub_f32_e32 v35, v35, v85
	v_sub_f32_e32 v34, v34, v85
	v_sub_f32_e32 v33, v33, v85
	v_sub_f32_e32 v32, v32, v85
	v_sub_f32_e32 v31, v31, v85
	v_sub_f32_e32 v30, v30, v85
	v_sub_f32_e32 v29, v29, v85
	v_sub_f32_e32 v28, v28, v85
	v_sub_f32_e32 v27, v27, v85
	v_sub_f32_e32 v26, v26, v85
	v_sub_f32_e32 v25, v25, v85
	v_sub_f32_e32 v24, v24, v85
	v_sub_f32_e32 v23, v23, v85
	v_sub_f32_e32 v22, v22, v85
	v_sub_f32_e32 v21, v21, v85
	v_sub_f32_e32 v20, v20, v85
	v_mul_f32_e32 v169, v169, v84
